# full stack, QK+DMA interleave, scalar DMA address setup moved behind the K read burst
# baseline (speedup 1.0000x reference)
.LBB0_185:
	s_waitcnt vmcnt(0)
	s_barrier
	v_mbcnt_lo_u32_b32 v192, -1, 0
	v_mbcnt_hi_u32_b32 v192, -1, v192
	v_ashrrev_i32_e32 v188, 5, v192
	v_and_b32_e32 v193, 31, v192
	v_lshlrev_b32_e32 v189, 4, v192
	v_lshlrev_b32_e32 v191, 4, v188
	v_lshlrev_b32_e32 v190, 8, v193
	v_bitop3_b32 v2, v189, v191, s48 bitop3:0x6c
	v_add3_u32 v6, s84, v2, v190
	v_add_u32_e32 v7, 32, v191
	v_bitop3_b32 v7, v7, v189, s48 bitop3:0x78
	v_add3_u32 v250, s84, v7, v190
	v_add_u32_e32 v7, 64, v191
	v_bitop3_b32 v7, v7, v189, s48 bitop3:0x78
	v_add3_u32 v222, s84, v7, v190
	v_add_u32_e32 v7, 0x60, v191
	v_bitop3_b32 v7, v7, v189, s48 bitop3:0x78
	v_add3_u32 v190, s84, v7, v190
	v_add_u32_e32 v189, s81, v189
	ds_read_b128 v[2:5], v6
	ds_read_b128 v[194:197], v6 offset:8192
	ds_read_b128 v[198:201], v250
	ds_read_b128 v[202:205], v250 offset:8192
	ds_read_b128 v[206:209], v222
	ds_read_b128 v[210:213], v222 offset:8192
	ds_read_b128 v[214:217], v190
	ds_read_b128 v[218:221], v190 offset:8192
	ds_read_b128 v[226:229], v6 offset:128
	ds_read_b128 v[230:233], v6 offset:8320
	s_add_i32 s35, 0, 0x10000
	s_add_i32 s37, s35, s61
	s_add_i32 s92, s37, 0x4000
	s_add_i32 s35, s35, s65
	s_add_i32 s93, s35, 0x4000
	s_add_u32 s98, s8, s14
	s_addc_u32 s99, s9, s15
	s_add_u32 s100, s8, s28
	s_addc_u32 s101, s9, s29
	s_add_i32 s36, s68, s79
	s_add_i32 s90, s36, 64
	s_add_i32 s34, s79, 63
	s_mul_hi_i32 s91, s90, 0xa000
	s_mul_i32 s90, s90, 0xa000
	s_add_u32 s90, s82, s90
	s_addc_u32 s91, s83, s91
	s_add_i32 s94, s47, s70
	s_add_i32 s95, s94, 0x380
	s_add_i32 s96, s47, s74
	s_add_i32 s97, s47, s77
	s_addk_i32 s97, 0xff80
	s_waitcnt lgkmcnt(9)
	s_mov_b32 m0, s37
	v_mfma_f32_32x32x16_bf16 v[18:33], v[2:5], v[34:37], 0
	global_load_lds_dwordx4 v251, s[98:99]
	s_waitcnt lgkmcnt(8)
	s_mov_b32 m0, s92
	v_mfma_f32_32x32x16_bf16 v[2:17], v[194:197], v[34:37], 0
	global_load_lds_dwordx4 v251, s[100:101]
	ds_read_b128 v[194:197], v250 offset:128
	s_waitcnt lgkmcnt(8)
	s_mov_b32 m0, s35
	v_mfma_f32_32x32x16_bf16 v[18:33], v[198:201], v[38:41], v[18:33]
	global_load_lds_dwordx4 v252, s[98:99]
	ds_read_b128 v[198:201], v250 offset:8320
	s_waitcnt lgkmcnt(8)
	s_mov_b32 m0, s93
	v_mfma_f32_32x32x16_bf16 v[2:17], v[202:205], v[38:41], v[2:17]
	global_load_lds_dwordx4 v252, s[100:101]
	ds_read_b128 v[202:205], v222 offset:128
	s_waitcnt lgkmcnt(8)
	s_mov_b32 m0, s94
	v_mfma_f32_32x32x16_bf16 v[18:33], v[206:209], v[42:45], v[18:33]
	global_load_lds_dwordx4 v253, s[90:91]
	ds_read_b128 v[206:209], v222 offset:8320
	s_waitcnt lgkmcnt(8)
	s_mov_b32 m0, s95
	v_mfma_f32_32x32x16_bf16 v[2:17], v[210:213], v[42:45], v[2:17]
	global_load_lds_dwordx4 v253, s[90:91] offset:128
	ds_read_b128 v[210:213], v190 offset:128
	s_waitcnt lgkmcnt(8)
	s_mov_b32 m0, s96
	v_mfma_f32_32x32x16_bf16 v[18:33], v[214:217], v[46:49], v[18:33]
	global_load_lds_dwordx4 v254, s[90:91]
	ds_read_b128 v[214:217], v190 offset:8320
	s_waitcnt lgkmcnt(8)
	s_mov_b32 m0, s97
	v_mfma_f32_32x32x16_bf16 v[2:17], v[218:221], v[46:49], v[2:17]
	global_load_lds_dwordx4 v254, s[90:91] offset:128
	ds_read_b128 v[218:221], v189
	s_waitcnt lgkmcnt(8)
	v_mfma_f32_32x32x16_bf16 v[18:33], v[226:229], v[50:53], v[18:33]
	ds_read_b128 v[226:229], v189 offset:1024
	s_waitcnt lgkmcnt(8)
	v_mfma_f32_32x32x16_bf16 v[2:17], v[230:233], v[50:53], v[2:17]
	s_waitcnt lgkmcnt(7)
	v_mfma_f32_32x32x16_bf16 v[18:33], v[194:197], v[54:57], v[18:33]
	s_waitcnt lgkmcnt(6)
	v_mfma_f32_32x32x16_bf16 v[2:17], v[198:201], v[54:57], v[2:17]
	s_waitcnt lgkmcnt(1)
	v_mfma_f32_32x32x16_bf16 v[18:33], v[202:205], v[218:221], v[18:33]
	v_mfma_f32_32x32x16_bf16 v[2:17], v[206:209], v[218:221], v[2:17]
	s_waitcnt lgkmcnt(0)
	v_mfma_f32_32x32x16_bf16 v[18:33], v[210:213], v[226:229], v[18:33]
	s_cmp_le_u32 s34, s59
	v_mfma_f32_32x32x16_bf16 v[2:17], v[214:217], v[226:229], v[2:17]
	s_cbranch_scc1 .LBB0_187
	v_lshlrev_b32_e32 v188, 2, v188
	v_sub_u32_e32 v188, v193, v188
	v_add_u32_e32 v188, s86, v188
	v_add_u32_e32 v189, 0x80000001, v188
	v_cmp_gt_u32_e32 vcc, s46, v189
	s_nop 4
	v_cndmask_b32_e32 v18, v225, v18, vcc
	v_cmp_lt_i32_e32 vcc, 31, v189
	s_nop 1
	v_cndmask_b32_e32 v2, v225, v2, vcc
	v_cmp_lt_i32_e32 vcc, 0, v189
	v_subrev_u32_e32 v189, 31, v188
	s_nop 0
	v_cndmask_b32_e32 v19, v225, v19, vcc
	v_cmp_lt_u32_e32 vcc, s49, v189
	v_subrev_u32_e32 v189, 32, v188
	s_nop 0
	v_cndmask_b32_e32 v3, v225, v3, vcc
	v_cmp_lt_u32_e32 vcc, s49, v188
	s_nop 1
	v_cndmask_b32_e32 v20, v225, v20, vcc
	v_cmp_lt_u32_e32 vcc, s49, v189
	v_add_u32_e32 v189, -1, v188
	s_nop 0
	v_cndmask_b32_e32 v4, v225, v4, vcc
	v_cmp_lt_u32_e32 vcc, s49, v189
	v_subrev_u32_e32 v189, 33, v188
	s_nop 0
	v_cndmask_b32_e32 v21, v225, v21, vcc
	v_cmp_lt_u32_e32 vcc, s49, v189
	v_add_u32_e32 v189, -6, v188
	s_nop 0
	v_cndmask_b32_e32 v5, v225, v5, vcc
	v_cmp_lt_u32_e32 vcc, s49, v189
	v_subrev_u32_e32 v189, 38, v188
	s_nop 0
	v_cndmask_b32_e32 v22, v225, v22, vcc
	v_cmp_lt_u32_e32 vcc, s49, v189
	v_add_u32_e32 v189, -7, v188
	s_nop 0
	v_cndmask_b32_e32 v6, v225, v6, vcc
	v_cmp_lt_u32_e32 vcc, s49, v189
	v_subrev_u32_e32 v189, 39, v188
	s_nop 0
	v_cndmask_b32_e32 v23, v225, v23, vcc
	v_cmp_lt_u32_e32 vcc, s49, v189
	v_add_u32_e32 v189, -8, v188
	s_nop 0
	v_cndmask_b32_e32 v7, v225, v7, vcc
	v_cmp_lt_u32_e32 vcc, s49, v189
	v_subrev_u32_e32 v189, 40, v188
	s_nop 0
	v_cndmask_b32_e32 v24, v225, v24, vcc
	v_cmp_lt_u32_e32 vcc, s49, v189
	v_add_u32_e32 v189, -9, v188
	s_nop 0
	v_cndmask_b32_e32 v8, v225, v8, vcc
	v_cmp_lt_u32_e32 vcc, s49, v189
	v_subrev_u32_e32 v189, 41, v188
	s_nop 0
	v_cndmask_b32_e32 v25, v225, v25, vcc
	v_cmp_lt_u32_e32 vcc, s49, v189
	v_add_u32_e32 v189, -14, v188
	s_nop 0
	v_cndmask_b32_e32 v9, v225, v9, vcc
	v_cmp_lt_u32_e32 vcc, s49, v189
	v_subrev_u32_e32 v189, 46, v188
	s_nop 0
	v_cndmask_b32_e32 v26, v225, v26, vcc
	v_cmp_lt_u32_e32 vcc, s49, v189
	v_add_u32_e32 v189, -15, v188
	s_nop 0
	v_cndmask_b32_e32 v10, v225, v10, vcc
	v_cmp_lt_u32_e32 vcc, s49, v189
	v_subrev_u32_e32 v189, 47, v188
	s_nop 0
	v_cndmask_b32_e32 v27, v225, v27, vcc
	v_cmp_lt_u32_e32 vcc, s49, v189
	v_add_u32_e32 v189, -16, v188
	s_nop 0
	v_cndmask_b32_e32 v11, v225, v11, vcc
	v_cmp_lt_u32_e32 vcc, s49, v189
	v_subrev_u32_e32 v189, 48, v188
	s_nop 0
	v_cndmask_b32_e32 v28, v225, v28, vcc
	v_cmp_lt_u32_e32 vcc, s49, v189
	v_subrev_u32_e32 v189, 17, v188
	s_nop 0
	v_cndmask_b32_e32 v12, v225, v12, vcc
	v_cmp_lt_u32_e32 vcc, s49, v189
	v_subrev_u32_e32 v189, 49, v188
	s_nop 0
	v_cndmask_b32_e32 v29, v225, v29, vcc
	v_cmp_lt_u32_e32 vcc, s49, v189
	v_subrev_u32_e32 v189, 22, v188
	s_nop 0
	v_cndmask_b32_e32 v13, v225, v13, vcc
	v_cmp_lt_u32_e32 vcc, s49, v189
	v_subrev_u32_e32 v189, 54, v188
	s_nop 0
	v_cndmask_b32_e32 v30, v225, v30, vcc
	v_cmp_lt_u32_e32 vcc, s49, v189
	v_subrev_u32_e32 v189, 23, v188
	s_nop 0
	v_cndmask_b32_e32 v14, v225, v14, vcc
	v_cmp_lt_u32_e32 vcc, s49, v189
	v_subrev_u32_e32 v189, 55, v188
	s_nop 0
	v_cndmask_b32_e32 v31, v225, v31, vcc
	v_cmp_lt_u32_e32 vcc, s49, v189
	v_subrev_u32_e32 v189, 24, v188
	s_nop 0
	v_cndmask_b32_e32 v15, v225, v15, vcc
	v_cmp_lt_u32_e32 vcc, s49, v189
	v_subrev_u32_e32 v189, 56, v188
	s_nop 0
	v_cndmask_b32_e32 v32, v225, v32, vcc
	v_cmp_lt_u32_e32 vcc, s49, v189
	v_subrev_u32_e32 v189, 25, v188
	v_subrev_u32_e32 v188, 57, v188
	v_cndmask_b32_e32 v16, v225, v16, vcc
	v_cmp_lt_u32_e32 vcc, s49, v189
	s_nop 1
	v_cndmask_b32_e32 v33, v225, v33, vcc
	v_cmp_lt_u32_e32 vcc, s49, v188
	s_nop 1
	v_cndmask_b32_e32 v17, v225, v17, vcc

.LBB0_192:
	s_cmp_lg_u32 0, -1
	s_cselect_b32 s34, 0, 0
	s_add_i32 s34, s34, 0x8000
	s_waitcnt lgkmcnt(0)
	v_add_u32_e32 v220, s34, v255
	v_xor_b32_e32 v221, 0x110, v220
	ds_read_b64_tr_b16 v[18:19], v220 offset:0
	ds_read_b64_tr_b16 v[20:21], v221 offset:0
	v_xor_b32_e32 v222, 32, v220
	ds_read_b64_tr_b16 v[22:23], v222 offset:0
	v_xor_b32_e32 v250, 32, v221
	ds_read_b64_tr_b16 v[24:25], v250 offset:0
	ds_read_b64_tr_b16 v[26:27], v220 offset:0x200
	ds_read_b64_tr_b16 v[28:29], v221 offset:0x200
	s_waitcnt lgkmcnt(4)
	v_permlane16_swap_b32_e32 v10, v14
	v_permlane16_swap_b32_e32 v11, v15
	v_permlane16_swap_b32_e32 v12, v16
	v_permlane16_swap_b32_e32 v13, v17
	v_permlane16_swap_b32_e32 v2, v6
	v_permlane16_swap_b32_e32 v3, v7
	v_permlane16_swap_b32_e32 v4, v8
	v_permlane16_swap_b32_e32 v5, v9
	v_mfma_f32_16x16x32_bf16 v[30:33], v[10:13], v[18:21], v[58:61]
	v_mfma_f32_16x16x32_bf16 v[18:21], v[14:17], v[18:21], v[178:181]
	ds_read_b64_tr_b16 v[58:59], v222 offset:0x200
	ds_read_b64_tr_b16 v[60:61], v250 offset:0x200
	s_waitcnt lgkmcnt(4)
	v_mfma_f32_16x16x32_bf16 v[62:65], v[10:13], v[22:25], v[62:65]
	v_mfma_f32_16x16x32_bf16 v[22:25], v[14:17], v[22:25], v[166:169]
	ds_read_b64_tr_b16 v[166:167], v220 offset:0x400
	ds_read_b64_tr_b16 v[168:169], v221 offset:0x400
	s_waitcnt lgkmcnt(4)
	v_mfma_f32_16x16x32_bf16 v[66:69], v[10:13], v[26:29], v[66:69]
	v_mfma_f32_16x16x32_bf16 v[26:29], v[14:17], v[26:29], v[162:165]
	ds_read_b64_tr_b16 v[162:163], v222 offset:0x400
	ds_read_b64_tr_b16 v[164:165], v250 offset:0x400
	s_waitcnt lgkmcnt(4)
	v_mfma_f32_16x16x32_bf16 v[70:73], v[10:13], v[58:61], v[70:73]
	v_mfma_f32_16x16x32_bf16 v[58:61], v[14:17], v[58:61], v[154:157]
	ds_read_b64_tr_b16 v[154:155], v220 offset:0x600
	ds_read_b64_tr_b16 v[156:157], v221 offset:0x600
	s_waitcnt lgkmcnt(4)
	v_mfma_f32_16x16x32_bf16 v[178:181], v[10:13], v[166:169], v[74:77]
	v_mfma_f32_16x16x32_bf16 v[150:153], v[14:17], v[166:169], v[150:153]
	ds_read_b64_tr_b16 v[74:75], v222 offset:0x600
	ds_read_b64_tr_b16 v[76:77], v250 offset:0x600
	s_waitcnt lgkmcnt(4)
	v_mfma_f32_16x16x32_bf16 v[166:169], v[10:13], v[162:165], v[82:85]
	v_mfma_f32_16x16x32_bf16 v[162:165], v[14:17], v[162:165], v[142:145]
	ds_read_b64_tr_b16 v[82:83], v220 offset:0x2000
	ds_read_b64_tr_b16 v[84:85], v221 offset:0x2000
	s_waitcnt lgkmcnt(4)
	v_mfma_f32_16x16x32_bf16 v[192:195], v[10:13], v[154:157], v[90:93]
	v_mfma_f32_16x16x32_bf16 v[154:157], v[14:17], v[154:157], v[138:141]
	ds_read_b64_tr_b16 v[90:91], v222 offset:0x2000
	ds_read_b64_tr_b16 v[92:93], v250 offset:0x2000
	s_waitcnt lgkmcnt(4)
	v_mfma_f32_16x16x32_bf16 v[196:199], v[10:13], v[74:77], v[98:101]
	v_mfma_f32_16x16x32_bf16 v[200:203], v[14:17], v[74:77], v[130:133]
	ds_read_b64_tr_b16 v[74:75], v220 offset:0x2200
	ds_read_b64_tr_b16 v[76:77], v221 offset:0x2200
	s_waitcnt lgkmcnt(4)
	v_mfma_f32_16x16x32_bf16 v[110:113], v[10:13], v[82:85], v[110:113]
	v_mfma_f32_16x16x32_bf16 v[126:129], v[14:17], v[82:85], v[126:129]
	ds_read_b64_tr_b16 v[82:83], v222 offset:0x2200
	ds_read_b64_tr_b16 v[84:85], v250 offset:0x2200
	s_waitcnt lgkmcnt(4)
	v_mfma_f32_16x16x32_bf16 v[122:125], v[10:13], v[90:93], v[122:125]
	v_mfma_f32_16x16x32_bf16 v[118:121], v[14:17], v[90:93], v[118:121]
	ds_read_b64_tr_b16 v[90:91], v220 offset:0x2400
	ds_read_b64_tr_b16 v[92:93], v221 offset:0x2400
	s_waitcnt lgkmcnt(4)
	v_mfma_f32_16x16x32_bf16 v[204:207], v[10:13], v[74:77], v[134:137]
	v_mfma_f32_16x16x32_bf16 v[208:211], v[14:17], v[74:77], v[114:117]
	ds_read_b64_tr_b16 v[74:75], v222 offset:0x2400
	ds_read_b64_tr_b16 v[76:77], v250 offset:0x2400
	s_waitcnt lgkmcnt(4)
	v_mfma_f32_16x16x32_bf16 v[212:215], v[10:13], v[82:85], v[146:149]
	v_mfma_f32_16x16x32_bf16 v[216:219], v[14:17], v[82:85], v[106:109]
	ds_read_b64_tr_b16 v[82:83], v220 offset:0x2600
	ds_read_b64_tr_b16 v[84:85], v221 offset:0x2600
	s_waitcnt lgkmcnt(4)
	v_mfma_f32_16x16x32_bf16 v[226:229], v[10:13], v[90:93], v[158:161]
	v_mfma_f32_16x16x32_bf16 v[230:233], v[14:17], v[90:93], v[102:105]
	ds_read_b64_tr_b16 v[90:91], v222 offset:0x2600
	ds_read_b64_tr_b16 v[92:93], v250 offset:0x2600
	s_waitcnt lgkmcnt(4)
	v_mfma_f32_16x16x32_bf16 v[234:237], v[10:13], v[74:77], v[174:177]
	v_mfma_f32_16x16x32_bf16 v[238:241], v[14:17], v[74:77], v[94:97]
	ds_read_b64_tr_b16 v[94:95], v220 offset:0x4000
	ds_read_b64_tr_b16 v[96:97], v221 offset:0x4000
	s_waitcnt lgkmcnt(4)
	v_mfma_f32_16x16x32_bf16 v[242:245], v[10:13], v[82:85], v[182:185]
	v_mfma_f32_16x16x32_bf16 v[246:249], v[14:17], v[82:85], v[86:89]
	ds_read_b64_tr_b16 v[82:83], v222 offset:0x4000
	ds_read_b64_tr_b16 v[84:85], v250 offset:0x4000
	s_waitcnt lgkmcnt(4)
	v_mfma_f32_16x16x32_bf16 v[10:13], v[10:13], v[90:93], v[170:173]
	v_mfma_f32_16x16x32_bf16 v[14:17], v[14:17], v[90:93], v[78:81]
	ds_read_b64_tr_b16 v[86:87], v220 offset:0x4200
	ds_read_b64_tr_b16 v[88:89], v221 offset:0x4200
	s_waitcnt lgkmcnt(4)
	v_mfma_f32_16x16x32_bf16 v[74:77], v[2:5], v[94:97], v[30:33]
	v_mfma_f32_16x16x32_bf16 v[130:133], v[6:9], v[94:97], v[18:21]
	ds_read_b64_tr_b16 v[18:19], v222 offset:0x4200
	ds_read_b64_tr_b16 v[20:21], v250 offset:0x4200
	s_waitcnt lgkmcnt(4)
	v_mfma_f32_16x16x32_bf16 v[78:81], v[2:5], v[82:85], v[62:65]
	v_mfma_f32_16x16x32_bf16 v[134:137], v[6:9], v[82:85], v[22:25]
	ds_read_b64_tr_b16 v[22:23], v220 offset:0x4400
	ds_read_b64_tr_b16 v[24:25], v221 offset:0x4400
	s_waitcnt lgkmcnt(4)
	v_mfma_f32_16x16x32_bf16 v[82:85], v[2:5], v[86:89], v[66:69]
	v_mfma_f32_16x16x32_bf16 v[138:141], v[6:9], v[86:89], v[26:29]
	ds_read_b64_tr_b16 v[26:27], v222 offset:0x4400
	ds_read_b64_tr_b16 v[28:29], v250 offset:0x4400
	s_waitcnt lgkmcnt(4)
	v_mfma_f32_16x16x32_bf16 v[86:89], v[2:5], v[18:21], v[70:73]
	v_mfma_f32_16x16x32_bf16 v[142:145], v[6:9], v[18:21], v[58:61]
	ds_read_b64_tr_b16 v[18:19], v220 offset:0x4600
	ds_read_b64_tr_b16 v[20:21], v221 offset:0x4600
	s_waitcnt lgkmcnt(4)
	v_mfma_f32_16x16x32_bf16 v[90:93], v[2:5], v[22:25], v[178:181]
	v_mfma_f32_16x16x32_bf16 v[146:149], v[6:9], v[22:25], v[150:153]
	ds_read_b64_tr_b16 v[22:23], v222 offset:0x4600
	ds_read_b64_tr_b16 v[24:25], v250 offset:0x4600
	s_waitcnt lgkmcnt(4)
	v_mfma_f32_16x16x32_bf16 v[94:97], v[2:5], v[26:29], v[166:169]
	v_mfma_f32_16x16x32_bf16 v[150:153], v[6:9], v[26:29], v[162:165]
	ds_read_b64_tr_b16 v[26:27], v220 offset:0x6000
	ds_read_b64_tr_b16 v[28:29], v221 offset:0x6000
	s_waitcnt lgkmcnt(4)
	v_mfma_f32_16x16x32_bf16 v[98:101], v[2:5], v[18:21], v[192:195]
	v_mfma_f32_16x16x32_bf16 v[154:157], v[6:9], v[18:21], v[154:157]
	ds_read_b64_tr_b16 v[18:19], v222 offset:0x6000
	ds_read_b64_tr_b16 v[20:21], v250 offset:0x6000
	s_waitcnt lgkmcnt(4)
	v_mfma_f32_16x16x32_bf16 v[102:105], v[2:5], v[22:25], v[196:199]
	v_mfma_f32_16x16x32_bf16 v[158:161], v[6:9], v[22:25], v[200:203]
	ds_read_b64_tr_b16 v[22:23], v220 offset:0x6200
	ds_read_b64_tr_b16 v[24:25], v221 offset:0x6200
	s_waitcnt lgkmcnt(4)
	v_mfma_f32_16x16x32_bf16 v[106:109], v[2:5], v[26:29], v[110:113]
	v_mfma_f32_16x16x32_bf16 v[162:165], v[6:9], v[26:29], v[126:129]
	ds_read_b64_tr_b16 v[26:27], v222 offset:0x6200
	ds_read_b64_tr_b16 v[28:29], v250 offset:0x6200
	s_waitcnt lgkmcnt(4)
	v_mfma_f32_16x16x32_bf16 v[110:113], v[2:5], v[18:21], v[122:125]
	v_mfma_f32_16x16x32_bf16 v[166:169], v[6:9], v[18:21], v[118:121]
	ds_read_b64_tr_b16 v[18:19], v220 offset:0x6400
	ds_read_b64_tr_b16 v[20:21], v221 offset:0x6400
	s_waitcnt lgkmcnt(4)
	v_mfma_f32_16x16x32_bf16 v[114:117], v[2:5], v[22:25], v[204:207]
	v_mfma_f32_16x16x32_bf16 v[170:173], v[6:9], v[22:25], v[208:211]
	ds_read_b64_tr_b16 v[22:23], v222 offset:0x6400
	ds_read_b64_tr_b16 v[24:25], v250 offset:0x6400
	s_waitcnt lgkmcnt(4)
	v_mfma_f32_16x16x32_bf16 v[118:121], v[2:5], v[26:29], v[212:215]
	v_mfma_f32_16x16x32_bf16 v[174:177], v[6:9], v[26:29], v[216:219]
	ds_read_b64_tr_b16 v[26:27], v220 offset:0x6600
	ds_read_b64_tr_b16 v[28:29], v221 offset:0x6600
	s_waitcnt lgkmcnt(4)
	v_mfma_f32_16x16x32_bf16 v[122:125], v[2:5], v[18:21], v[226:229]
	v_mfma_f32_16x16x32_bf16 v[178:181], v[6:9], v[18:21], v[230:233]
	ds_read_b64_tr_b16 v[18:19], v222 offset:0x6600
	ds_read_b64_tr_b16 v[20:21], v250 offset:0x6600
	s_waitcnt lgkmcnt(4)
	v_mfma_f32_16x16x32_bf16 v[126:129], v[2:5], v[22:25], v[234:237]
	v_mfma_f32_16x16x32_bf16 v[182:185], v[6:9], v[22:25], v[238:241]
	s_waitcnt lgkmcnt(2)
	v_mfma_f32_16x16x32_bf16 v[66:69], v[2:5], v[26:29], v[242:245]
	v_mfma_f32_16x16x32_bf16 v[70:73], v[6:9], v[26:29], v[246:249]
	s_waitcnt lgkmcnt(0)
	v_mfma_f32_16x16x32_bf16 v[58:61], v[2:5], v[18:21], v[10:13]
	v_mfma_f32_16x16x32_bf16 v[62:65], v[6:9], v[18:21], v[14:17]
	s_cmp_ge_u32 s89, s80
	s_waitcnt vmcnt(0)
	s_barrier
	s_cselect_b64 s[34:35], -1, 0
	s_and_b64 vcc, exec, s[34:35]
	v_mbcnt_lo_u32_b32 v192, -1, 0
	v_mbcnt_hi_u32_b32 v192, -1, v192
	s_cbranch_vccnz .LBB0_194
	v_ashrrev_i32_e32 v193, 5, v192
	v_and_b32_e32 v194, 31, v192
	v_lshlrev_b32_e32 v195, 4, v192
	v_lshlrev_b32_e32 v221, 4, v193
	v_lshlrev_b32_e32 v220, 8, v194
	v_bitop3_b32 v2, v195, v221, s48 bitop3:0x6c
	v_add3_u32 v6, s85, v2, v220
	v_add_u32_e32 v7, 32, v221
	v_bitop3_b32 v7, v7, v195, s48 bitop3:0x78
	v_add3_u32 v250, s85, v7, v220
	v_add_u32_e32 v7, 64, v221
	v_bitop3_b32 v7, v7, v195, s48 bitop3:0x78
	v_add3_u32 v222, s85, v7, v220
	v_add_u32_e32 v7, 0x60, v221
	v_bitop3_b32 v7, v7, v195, s48 bitop3:0x78
	v_add3_u32 v220, s85, v7, v220
	v_add_u32_e32 v195, s81, v195
	ds_read_b128 v[2:5], v6
	ds_read_b128 v[196:199], v6 offset:8192
	ds_read_b128 v[200:203], v250
	ds_read_b128 v[204:207], v250 offset:8192
	ds_read_b128 v[208:211], v222
	ds_read_b128 v[212:215], v222 offset:8192
	ds_read_b128 v[216:219], v220
	ds_read_b128 v[226:229], v220 offset:8192
	ds_read_b128 v[230:233], v6 offset:128
	ds_read_b128 v[234:237], v6 offset:8320
	s_add_u32 s98, s8, s30
	s_addc_u32 s99, s9, s31
	s_addk_i32 s36, 0x80
	s_mul_hi_i32 s37, s36, 0xa000
	s_mul_i32 s36, s36, 0xa000
	s_add_u32 s36, s82, s36
	s_addc_u32 s37, s83, s37
	s_add_i32 s100, s72, 0xffffff80
	s_add_i32 s101, s78, 0xffffff80
	s_waitcnt lgkmcnt(9)
	s_mov_b32 m0, s62
	v_mfma_f32_32x32x16_bf16 v[18:33], v[2:5], v[34:37], 0
	global_load_lds_dwordx4 v251, s[98:99]
	s_waitcnt lgkmcnt(8)
	s_mov_b32 m0, s63
	v_mfma_f32_32x32x16_bf16 v[2:17], v[196:199], v[34:37], 0
	global_load_lds_dwordx4 v251, s[8:9]
	ds_read_b128 v[196:199], v250 offset:128
	s_waitcnt lgkmcnt(8)
	s_mov_b32 m0, s66
	v_mfma_f32_32x32x16_bf16 v[18:33], v[200:203], v[38:41], v[18:33]
	global_load_lds_dwordx4 v252, s[98:99]
	ds_read_b128 v[200:203], v250 offset:8320
	s_waitcnt lgkmcnt(8)
	s_mov_b32 m0, s67
	v_mfma_f32_32x32x16_bf16 v[2:17], v[204:207], v[38:41], v[2:17]
	global_load_lds_dwordx4 v252, s[8:9]
	ds_read_b128 v[204:207], v222 offset:128
	s_waitcnt lgkmcnt(8)
	s_mov_b32 m0, s71
	v_mfma_f32_32x32x16_bf16 v[18:33], v[208:211], v[42:45], v[18:33]
	global_load_lds_dwordx4 v253, s[36:37]
	ds_read_b128 v[208:211], v222 offset:8320
	s_waitcnt lgkmcnt(8)
	s_mov_b32 m0, s100
	v_mfma_f32_32x32x16_bf16 v[2:17], v[212:215], v[42:45], v[2:17]
	global_load_lds_dwordx4 v253, s[36:37] offset:128
	ds_read_b128 v[212:215], v220 offset:128
	s_waitcnt lgkmcnt(8)
	s_mov_b32 m0, s75
	v_mfma_f32_32x32x16_bf16 v[18:33], v[216:219], v[46:49], v[18:33]
	global_load_lds_dwordx4 v254, s[36:37]
	ds_read_b128 v[216:219], v220 offset:8320
	s_waitcnt lgkmcnt(8)
	s_mov_b32 m0, s101
	v_mfma_f32_32x32x16_bf16 v[2:17], v[226:229], v[46:49], v[2:17]
	global_load_lds_dwordx4 v254, s[36:37] offset:128
	ds_read_b128 v[226:229], v195
	s_waitcnt lgkmcnt(8)
	v_mfma_f32_32x32x16_bf16 v[18:33], v[230:233], v[50:53], v[18:33]
	ds_read_b128 v[230:233], v195 offset:1024
	s_waitcnt lgkmcnt(8)
	v_mfma_f32_32x32x16_bf16 v[2:17], v[234:237], v[50:53], v[2:17]
	s_waitcnt lgkmcnt(7)
	v_mfma_f32_32x32x16_bf16 v[18:33], v[196:199], v[54:57], v[18:33]
	s_waitcnt lgkmcnt(6)
	v_mfma_f32_32x32x16_bf16 v[2:17], v[200:203], v[54:57], v[2:17]
	s_waitcnt lgkmcnt(1)
	v_mfma_f32_32x32x16_bf16 v[18:33], v[204:207], v[226:229], v[18:33]
	v_mfma_f32_32x32x16_bf16 v[2:17], v[208:211], v[226:229], v[2:17]
	s_waitcnt lgkmcnt(0)
	v_mfma_f32_32x32x16_bf16 v[18:33], v[212:215], v[230:233], v[18:33]
	s_add_i32 s36, s79, 0x7f
	s_cmp_le_u32 s36, s59
	v_mfma_f32_32x32x16_bf16 v[2:17], v[216:219], v[230:233], v[2:17]
	s_branch .Lqk1_join
